# diagonal-tile decay clamp folded into the exp2 (v_exp clamp replaces v_min 0), 32 sites; rest as branch-free diagonal-tile version
# baseline (speedup 1.0000x reference)
.LBB0_1746:
	v_max_f32_e32 v77, v77, v77
	v_max_f32_e32 v77, 0xda24260, v77
	v_rcp_f32_e32 v77, v77
	s_andn2_b64 vcc, exec, s[42:43]
	v_mul_f32_e32 v77, v1, v77
	s_cbranch_vccnz .LBB0_1780
	v_sub_f32_e32 v212, v76, v72
	v_cmp_gt_u32_e64 s[2:3], v86, v115
	v_cmp_eq_u32_e32 vcc, v115, v86
	v_exp_f32_e64 v212, v212 clamp
	v_add_f32_e32 v213, v77, v84
	v_mul_f32_e32 v212, v212, v84
	v_cndmask_b32_e64 v212, 0, v212, s[2:3]
	v_cndmask_b32_e32 v2, v212, v213, vcc
	v_sub_f32_e32 v214, v76, v73
	v_cmp_gt_u32_e64 s[2:3], v86, v129
	v_cmp_eq_u32_e32 vcc, v129, v86
	v_exp_f32_e64 v214, v214 clamp
	v_add_f32_e32 v215, v77, v85
	v_mul_f32_e32 v214, v214, v85
	v_cndmask_b32_e64 v214, 0, v214, s[2:3]
	v_cndmask_b32_e32 v3, v214, v215, vcc
	v_sub_f32_e32 v216, v76, v74
	v_cmp_gt_u32_e64 s[2:3], v86, v130
	v_cmp_eq_u32_e32 vcc, v130, v86
	v_exp_f32_e64 v216, v216 clamp
	v_add_f32_e32 v217, v77, v82
	v_mul_f32_e32 v216, v216, v82
	v_cndmask_b32_e64 v216, 0, v216, s[2:3]
	v_cndmask_b32_e32 v4, v216, v217, vcc
	v_sub_f32_e32 v218, v76, v75
	v_cmp_gt_u32_e64 s[2:3], v86, v131
	v_cmp_eq_u32_e32 vcc, v131, v86
	v_exp_f32_e64 v218, v218 clamp
	v_add_f32_e32 v219, v77, v83
	v_mul_f32_e32 v218, v218, v83
	v_cndmask_b32_e64 v218, 0, v218, s[2:3]
	v_cndmask_b32_e32 v5, v218, v219, vcc
	v_sub_f32_e32 v212, v76, v68
	v_cmp_gt_u32_e64 s[2:3], v86, v132
	v_cmp_eq_u32_e32 vcc, v132, v86
	v_exp_f32_e64 v212, v212 clamp
	v_add_f32_e32 v213, v77, v80
	v_mul_f32_e32 v212, v212, v80
	v_cndmask_b32_e64 v212, 0, v212, s[2:3]
	v_cndmask_b32_e32 v6, v212, v213, vcc
	v_sub_f32_e32 v214, v76, v69
	v_cmp_gt_u32_e64 s[2:3], v86, v133
	v_cmp_eq_u32_e32 vcc, v133, v86
	v_exp_f32_e64 v214, v214 clamp
	v_add_f32_e32 v215, v77, v81
	v_mul_f32_e32 v214, v214, v81
	v_cndmask_b32_e64 v214, 0, v214, s[2:3]
	v_cndmask_b32_e32 v7, v214, v215, vcc
	v_sub_f32_e32 v216, v76, v70
	v_cmp_gt_u32_e64 s[2:3], v86, v134
	v_cmp_eq_u32_e32 vcc, v134, v86
	v_exp_f32_e64 v216, v216 clamp
	v_add_f32_e32 v217, v77, v78
	v_mul_f32_e32 v216, v216, v78
	v_cndmask_b32_e64 v216, 0, v216, s[2:3]
	v_cndmask_b32_e32 v8, v216, v217, vcc
	v_sub_f32_e32 v218, v76, v71
	v_cmp_gt_u32_e64 s[2:3], v86, v135
	v_cmp_eq_u32_e32 vcc, v135, v86
	v_exp_f32_e64 v218, v218 clamp
	v_add_f32_e32 v219, v77, v79
	v_mul_f32_e32 v218, v218, v79
	v_cndmask_b32_e64 v218, 0, v218, s[2:3]
	v_cndmask_b32_e32 v9, v218, v219, vcc
.LBB0_1780:
	v_cvt_pk_bf16_f32 v2, v2, v3
	v_cvt_pk_bf16_f32 v3, v4, v5
	v_cvt_pk_bf16_f32 v4, v6, v7
	v_cvt_pk_bf16_f32 v5, v8, v9
	s_and_b64 vcc, exec, s[10:11]
	s_nop 0
	v_mfma_f32_16x16x32_bf16 v[2:5], v[24:27], v[2:5], 0
	s_cbranch_vccz .LBB0_1814
	ds_read_b128 v[68:71], v182 offset:128
	ds_read_b128 v[6:9], v182 offset:192
	v_lshlrev_b32_e32 v73, 16, v64
	s_waitcnt lgkmcnt(0)
	v_sub_f32_e32 v212, v76, v68
	v_cmp_gt_u32_e64 s[2:3], v86, v136
	v_cmp_eq_u32_e32 vcc, v136, v86
	v_exp_f32_e64 v212, v212 clamp
	v_add_f32_e32 v213, v77, v73
	v_mul_f32_e32 v212, v212, v73
	v_cndmask_b32_e64 v212, 0, v212, s[2:3]
	v_cndmask_b32_e32 v72, v212, v213, vcc
.LBB0_1785:
	s_waitcnt lgkmcnt(0)
	v_and_b32_e32 v68, 0xffff0000, v64
	v_sub_f32_e32 v214, v76, v69
	v_cmp_gt_u32_e64 s[2:3], v86, v137
	v_cmp_eq_u32_e32 vcc, v137, v86
	v_exp_f32_e64 v214, v214 clamp
	v_add_f32_e32 v215, v77, v68
	v_mul_f32_e32 v214, v214, v68
	v_cndmask_b32_e64 v214, 0, v214, s[2:3]
	v_cndmask_b32_e32 v64, v214, v215, vcc
	v_lshlrev_b32_e32 v68, 16, v65
	v_sub_f32_e32 v216, v76, v70
	v_cmp_gt_u32_e64 s[2:3], v86, v138
	v_cmp_eq_u32_e32 vcc, v138, v86
	v_exp_f32_e64 v216, v216 clamp
	v_add_f32_e32 v217, v77, v68
	v_mul_f32_e32 v216, v216, v68
	v_cndmask_b32_e64 v216, 0, v216, s[2:3]
	v_cndmask_b32_e32 v73, v216, v217, vcc
	v_and_b32_e32 v68, 0xffff0000, v65
	v_sub_f32_e32 v218, v76, v71
	v_cmp_gt_u32_e64 s[2:3], v86, v139
	v_cmp_eq_u32_e32 vcc, v139, v86
	v_exp_f32_e64 v218, v218 clamp
	v_add_f32_e32 v219, v77, v68
	v_mul_f32_e32 v218, v218, v68
	v_cndmask_b32_e64 v218, 0, v218, s[2:3]
	v_cndmask_b32_e32 v65, v218, v219, vcc
	v_lshlrev_b32_e32 v69, 16, v66
	v_sub_f32_e32 v212, v76, v6
	v_cmp_gt_u32_e64 s[2:3], v86, v140
	v_cmp_eq_u32_e32 vcc, v140, v86
	v_exp_f32_e64 v212, v212 clamp
	v_add_f32_e32 v213, v77, v69
	v_mul_f32_e32 v212, v212, v69
	v_cndmask_b32_e64 v212, 0, v212, s[2:3]
	v_cndmask_b32_e32 v68, v212, v213, vcc
	v_and_b32_e32 v6, 0xffff0000, v66
	v_sub_f32_e32 v214, v76, v7
	v_cmp_gt_u32_e64 s[2:3], v86, v141
	v_cmp_eq_u32_e32 vcc, v141, v86
	v_exp_f32_e64 v214, v214 clamp
	v_add_f32_e32 v215, v77, v6
	v_mul_f32_e32 v214, v214, v6
	v_cndmask_b32_e64 v214, 0, v214, s[2:3]
	v_cndmask_b32_e32 v66, v214, v215, vcc
	v_lshlrev_b32_e32 v6, 16, v67
	v_sub_f32_e32 v216, v76, v8
	v_cmp_gt_u32_e64 s[2:3], v86, v142
	v_cmp_eq_u32_e32 vcc, v142, v86
	v_exp_f32_e64 v216, v216 clamp
	v_add_f32_e32 v217, v77, v6
	v_mul_f32_e32 v216, v216, v6
	v_cndmask_b32_e64 v216, 0, v216, s[2:3]
	v_cndmask_b32_e32 v69, v216, v217, vcc
	v_and_b32_e32 v6, 0xffff0000, v67
	v_sub_f32_e32 v218, v76, v9
	v_cmp_gt_u32_e64 s[2:3], v86, v143
	v_cmp_eq_u32_e32 vcc, v143, v86
	v_exp_f32_e64 v218, v218 clamp
	v_add_f32_e32 v219, v77, v6
	v_mul_f32_e32 v218, v218, v6
	v_cndmask_b32_e64 v218, 0, v218, s[2:3]
	v_cndmask_b32_e32 v67, v218, v219, vcc
	v_cvt_pk_bf16_f32 v6, v72, v64
	v_cvt_pk_bf16_f32 v7, v73, v65
	v_cvt_pk_bf16_f32 v8, v68, v66
	v_cvt_pk_bf16_f32 v9, v69, v67
	s_nop 1
	v_mfma_f32_16x16x32_bf16 v[6:9], v[20:23], v[6:9], v[2:5]
	s_branch .LBB0_1816

.LBB0_1818:
	v_max_f32_e32 v117, v117, v117
	v_max_f32_e32 v117, 0xda24260, v117
	v_rcp_f32_e32 v117, v117
	s_andn2_b64 vcc, exec, s[72:73]
	v_mul_f32_e32 v117, v1, v117
	s_cbranch_vccnz .LBB0_1852
	s_waitcnt lgkmcnt(0)
	v_sub_f32_e32 v212, v116, v64
	v_cmp_gt_u32_e64 s[2:3], v183, v144
	v_cmp_eq_u32_e32 vcc, v144, v183
	v_exp_f32_e64 v212, v212 clamp
	v_add_f32_e32 v213, v117, v124
	v_mul_f32_e32 v212, v212, v124
	v_cndmask_b32_e64 v212, 0, v212, s[2:3]
	v_cndmask_b32_e32 v2, v212, v213, vcc
.LBB0_1823:
	s_waitcnt lgkmcnt(0)
	v_sub_f32_e32 v214, v116, v65
	v_cmp_gt_u32_e64 s[2:3], v183, v145
	v_cmp_eq_u32_e32 vcc, v145, v183
	v_exp_f32_e64 v214, v214 clamp
	v_add_f32_e32 v215, v117, v125
	v_mul_f32_e32 v214, v214, v125
	v_cndmask_b32_e64 v214, 0, v214, s[2:3]
	v_cndmask_b32_e32 v3, v214, v215, vcc
.LBB0_1827:
	s_waitcnt lgkmcnt(0)
	v_sub_f32_e32 v216, v116, v66
	v_cmp_gt_u32_e64 s[2:3], v183, v146
	v_cmp_eq_u32_e32 vcc, v146, v183
	v_exp_f32_e64 v216, v216 clamp
	v_add_f32_e32 v217, v117, v122
	v_mul_f32_e32 v216, v216, v122
	v_cndmask_b32_e64 v216, 0, v216, s[2:3]
	v_cndmask_b32_e32 v4, v216, v217, vcc
.LBB0_1831:
	s_waitcnt lgkmcnt(0)
	v_sub_f32_e32 v218, v116, v67
	v_cmp_gt_u32_e64 s[2:3], v183, v147
	v_cmp_eq_u32_e32 vcc, v147, v183
	v_exp_f32_e64 v218, v218 clamp
	v_add_f32_e32 v219, v117, v123
	v_mul_f32_e32 v218, v218, v123
	v_cndmask_b32_e64 v218, 0, v218, s[2:3]
	v_cndmask_b32_e32 v5, v218, v219, vcc
.LBB0_1835:
	s_waitcnt lgkmcnt(0)
	v_sub_f32_e32 v212, v116, v52
	v_cmp_gt_u32_e64 s[2:3], v183, v148
	v_cmp_eq_u32_e32 vcc, v148, v183
	v_exp_f32_e64 v212, v212 clamp
	v_add_f32_e32 v213, v117, v120
	v_mul_f32_e32 v212, v212, v120
	v_cndmask_b32_e64 v212, 0, v212, s[2:3]
	v_cndmask_b32_e32 v6, v212, v213, vcc
.LBB0_1839:
	s_waitcnt lgkmcnt(0)
	v_sub_f32_e32 v214, v116, v53
	v_cmp_gt_u32_e64 s[2:3], v183, v149
	v_cmp_eq_u32_e32 vcc, v149, v183
	v_exp_f32_e64 v214, v214 clamp
	v_add_f32_e32 v215, v117, v121
	v_mul_f32_e32 v214, v214, v121
	v_cndmask_b32_e64 v214, 0, v214, s[2:3]
	v_cndmask_b32_e32 v7, v214, v215, vcc
.LBB0_1843:
	s_waitcnt lgkmcnt(0)
	v_sub_f32_e32 v216, v116, v54
	v_cmp_gt_u32_e64 s[2:3], v183, v151
	v_cmp_eq_u32_e32 vcc, v151, v183
	v_exp_f32_e64 v216, v216 clamp
	v_add_f32_e32 v217, v117, v118
	v_mul_f32_e32 v216, v216, v118
	v_cndmask_b32_e64 v216, 0, v216, s[2:3]
	v_cndmask_b32_e32 v8, v216, v217, vcc
.LBB0_1847:
	s_waitcnt lgkmcnt(0)
	v_sub_f32_e32 v218, v116, v55
	v_cmp_gt_u32_e64 s[2:3], v183, v161
	v_cmp_eq_u32_e32 vcc, v161, v183
	v_exp_f32_e64 v218, v218 clamp
	v_add_f32_e32 v219, v117, v119
	v_mul_f32_e32 v218, v218, v119
	v_cndmask_b32_e64 v218, 0, v218, s[2:3]
	v_cndmask_b32_e32 v9, v218, v219, vcc
.LBB0_1851:
.LBB0_1852:
	v_cvt_pk_bf16_f32 v2, v2, v3
	v_cvt_pk_bf16_f32 v3, v4, v5
	v_cvt_pk_bf16_f32 v4, v6, v7
	v_cvt_pk_bf16_f32 v5, v8, v9
	s_and_b64 vcc, exec, s[42:43]
	s_nop 0
	v_mfma_f32_16x16x32_bf16 v[2:5], v[16:19], v[2:5], v[84:87]
	s_cbranch_vccnz .LBB0_1886
	s_nop 1
	ds_read_b128 v[84:87], v182 offset:384
	ds_read_b128 v[6:9], v182 offset:448
	v_lshlrev_b32_e32 v119, 16, v80
	s_waitcnt lgkmcnt(0)
	v_sub_f32_e32 v212, v116, v84
	v_cmp_gt_u32_e64 s[2:3], v183, v166
	v_cmp_eq_u32_e32 vcc, v166, v183
	v_exp_f32_e64 v212, v212 clamp
	v_add_f32_e32 v213, v117, v119
	v_mul_f32_e32 v212, v212, v119
	v_cndmask_b32_e64 v212, 0, v212, s[2:3]
	v_cndmask_b32_e32 v118, v212, v213, vcc
.LBB0_1857:
	s_waitcnt lgkmcnt(0)
	v_and_b32_e32 v84, 0xffff0000, v80
	v_sub_f32_e32 v214, v116, v85
	v_cmp_gt_u32_e64 s[2:3], v183, v167
	v_cmp_eq_u32_e32 vcc, v167, v183
	v_exp_f32_e64 v214, v214 clamp
	v_add_f32_e32 v215, v117, v84
	v_mul_f32_e32 v214, v214, v84
	v_cndmask_b32_e64 v214, 0, v214, s[2:3]
	v_cndmask_b32_e32 v80, v214, v215, vcc
	v_lshlrev_b32_e32 v84, 16, v81
	v_sub_f32_e32 v216, v116, v86
	v_cmp_gt_u32_e64 s[2:3], v183, v168
	v_cmp_eq_u32_e32 vcc, v168, v183
	v_exp_f32_e64 v216, v216 clamp
	v_add_f32_e32 v217, v117, v84
	v_mul_f32_e32 v216, v216, v84
	v_cndmask_b32_e64 v216, 0, v216, s[2:3]
	v_cndmask_b32_e32 v119, v216, v217, vcc
	v_and_b32_e32 v84, 0xffff0000, v81
	v_sub_f32_e32 v218, v116, v87
	v_cmp_gt_u32_e64 s[2:3], v183, v169
	v_cmp_eq_u32_e32 vcc, v169, v183
	v_exp_f32_e64 v218, v218 clamp
	v_add_f32_e32 v219, v117, v84
	v_mul_f32_e32 v218, v218, v84
	v_cndmask_b32_e64 v218, 0, v218, s[2:3]
	v_cndmask_b32_e32 v81, v218, v219, vcc
	v_lshlrev_b32_e32 v85, 16, v82
	v_sub_f32_e32 v212, v116, v6
	v_cmp_gt_u32_e64 s[2:3], v183, v170
	v_cmp_eq_u32_e32 vcc, v170, v183
	v_exp_f32_e64 v212, v212 clamp
	v_add_f32_e32 v213, v117, v85
	v_mul_f32_e32 v212, v212, v85
	v_cndmask_b32_e64 v212, 0, v212, s[2:3]
	v_cndmask_b32_e32 v84, v212, v213, vcc
	v_and_b32_e32 v6, 0xffff0000, v82
	v_sub_f32_e32 v214, v116, v7
	v_cmp_gt_u32_e64 s[2:3], v183, v171
	v_cmp_eq_u32_e32 vcc, v171, v183
	v_exp_f32_e64 v214, v214 clamp
	v_add_f32_e32 v215, v117, v6
	v_mul_f32_e32 v214, v214, v6
	v_cndmask_b32_e64 v214, 0, v214, s[2:3]
	v_cndmask_b32_e32 v82, v214, v215, vcc
	v_lshlrev_b32_e32 v6, 16, v83
	v_sub_f32_e32 v216, v116, v8
	v_cmp_gt_u32_e64 s[2:3], v183, v172
	v_cmp_eq_u32_e32 vcc, v172, v183
	v_exp_f32_e64 v216, v216 clamp
	v_add_f32_e32 v217, v117, v6
	v_mul_f32_e32 v216, v216, v6
	v_cndmask_b32_e64 v216, 0, v216, s[2:3]
	v_cndmask_b32_e32 v85, v216, v217, vcc
	v_and_b32_e32 v6, 0xffff0000, v83
	v_sub_f32_e32 v218, v116, v9
	v_cmp_gt_u32_e64 s[2:3], v183, v173
	v_cmp_eq_u32_e32 vcc, v173, v183
	v_exp_f32_e64 v218, v218 clamp
	v_add_f32_e32 v219, v117, v6
	v_mul_f32_e32 v218, v218, v6
	v_cndmask_b32_e64 v218, 0, v218, s[2:3]
	v_cndmask_b32_e32 v83, v218, v219, vcc
	v_cvt_pk_bf16_f32 v6, v118, v80
	v_cvt_pk_bf16_f32 v7, v119, v81
	v_cvt_pk_bf16_f32 v8, v84, v82
	v_cvt_pk_bf16_f32 v9, v85, v83
	s_nop 1
	v_mfma_f32_16x16x32_bf16 v[2:5], v[12:15], v[6:9], v[2:5]
